# QKV epilogue stores transposed through the wave-private LDS slab: 16 rows x 64 B per store instead of 64 rows x 16 B
# speedup vs baseline: 1.0481x; 1.0095x over previous
.LBB0_306:
	s_waitcnt lgkmcnt(0)
	v_pk_mul_f32 v[64:65], v[160:161], v[120:121] op_sel_hi:[0,1]
	v_pk_mul_f32 v[66:67], v[160:161], v[122:123] op_sel_hi:[0,1]
	s_lshl_b32 s36, s18, 6
	v_cvt_pk_bf16_f32 v64, v64, v65
	v_cvt_pk_bf16_f32 v65, v66, v67
	v_pk_mul_f32 v[66:67], v[160:161], v[108:109] op_sel_hi:[0,1]
	v_pk_mul_f32 v[70:71], v[160:161], v[118:119] op_sel_hi:[0,1]
	v_lshl_add_u64 v[68:69], v[126:127], 0, s[36:37]
	v_cvt_pk_bf16_f32 v66, v66, v67
	v_cvt_pk_bf16_f32 v67, v70, v71
	v_lshl_add_u32 v220, s36, 1, v176
	ds_write_b128 v220, v[64:67]
	v_pk_mul_f32 v[70:71], v[160:161], v[106:107] op_sel_hi:[0,1]
	s_xor_b64 s[8:9], s[6:7], -1
	v_pk_mul_f32 v[64:65], v[160:161], v[112:113] op_sel_hi:[0,1]
	v_pk_mul_f32 v[66:67], v[160:161], v[114:115] op_sel_hi:[0,1]
	v_cvt_pk_bf16_f32 v64, v64, v65
	v_cvt_pk_bf16_f32 v65, v66, v67
	v_pk_mul_f32 v[66:67], v[160:161], v[104:105] op_sel_hi:[0,1]
	v_cvt_pk_bf16_f32 v66, v66, v67
	v_cvt_pk_bf16_f32 v67, v70, v71
	ds_write_b128 v220, v[64:67] offset:16
	v_pk_mul_f32 v[70:71], v[160:161], v[110:111] op_sel_hi:[0,1]
	s_mov_b32 s18, 1
	v_pk_mul_f32 v[64:65], v[160:161], v[156:157] op_sel_hi:[0,1]
	v_pk_mul_f32 v[66:67], v[160:161], v[158:159] op_sel_hi:[0,1]
	v_cvt_pk_bf16_f32 v64, v64, v65
	v_cvt_pk_bf16_f32 v65, v66, v67
	v_pk_mul_f32 v[66:67], v[160:161], v[116:117] op_sel_hi:[0,1]
	v_cvt_pk_bf16_f32 v66, v66, v67
	v_cvt_pk_bf16_f32 v67, v70, v71
	ds_write_b128 v220, v[64:67] offset:32
	v_pk_mul_f32 v[70:71], v[160:161], v[98:99] op_sel_hi:[0,1]
	s_mov_b64 s[6:7], 0
	v_pk_mul_f32 v[64:65], v[160:161], v[100:101] op_sel_hi:[0,1]
	v_pk_mul_f32 v[66:67], v[160:161], v[102:103] op_sel_hi:[0,1]
	v_cvt_pk_bf16_f32 v64, v64, v65
	v_cvt_pk_bf16_f32 v65, v66, v67
	v_pk_mul_f32 v[66:67], v[160:161], v[96:97] op_sel_hi:[0,1]
	v_cvt_pk_bf16_f32 v66, v66, v67
	v_cvt_pk_bf16_f32 v67, v70, v71
	s_and_b64 vcc, exec, s[8:9]
	v_mov_b32_e32 v173, v244
	ds_write_b128 v220, v[64:67] offset:48
	v_mbcnt_lo_u32_b32 v204, -1, 0
	v_mbcnt_hi_u32_b32 v204, -1, v204
	v_lshrrev_b32_e32 v211, 2, v204
	v_and_b32_e32 v212, 3, v204
	v_sub_u32_e32 v216, v211, v204
	v_mul_i32_i24_e32 v224, 0x110, v216
	v_lshl_add_u32 v224, v212, 4, v224
	v_add_u32_e32 v224, v224, v220
	v_mul_i32_i24_e32 v234, 0x1600, v216
	v_lshl_add_u32 v234, v212, 4, v234
	s_waitcnt lgkmcnt(0)
	ds_read_b128 v[96:99], v224
	ds_read_b128 v[100:103], v224 offset:4352
	ds_read_b128 v[104:107], v224 offset:8704
	ds_read_b128 v[108:111], v224 offset:13056
	v_ashrrev_i32_e32 v235, 31, v234
	v_lshl_add_u64 v[250:251], v[68:69], 0, v[234:235]
	v_add_u32_e32 v234, 0x16000, v234
	s_waitcnt lgkmcnt(3)
	global_store_dwordx4 v[250:251], v[96:99], off
	v_ashrrev_i32_e32 v235, 31, v234
	v_lshl_add_u64 v[250:251], v[68:69], 0, v[234:235]
	v_add_u32_e32 v234, 0x16000, v234
	s_waitcnt lgkmcnt(2)
	global_store_dwordx4 v[250:251], v[100:103], off
	v_ashrrev_i32_e32 v235, 31, v234
	v_lshl_add_u64 v[250:251], v[68:69], 0, v[234:235]
	v_add_u32_e32 v234, 0x16000, v234
	s_waitcnt lgkmcnt(1)
	global_store_dwordx4 v[250:251], v[104:107], off
	v_ashrrev_i32_e32 v235, 31, v234
	v_lshl_add_u64 v[250:251], v[68:69], 0, v[234:235]
	s_waitcnt lgkmcnt(0)
	global_store_dwordx4 v[250:251], v[108:111], off
	s_cbranch_vccnz .LBB0_321

.LBB0_324:
	s_waitcnt lgkmcnt(0)
	v_pk_mul_f32 v[0:1], v[96:97], v[56:57] op_sel_hi:[0,1]
	v_pk_mul_f32 v[2:3], v[96:97], v[58:59] op_sel_hi:[0,1]
	s_lshl_b32 s36, s8, 6
	v_cvt_pk_bf16_f32 v0, v0, v1
	v_cvt_pk_bf16_f32 v1, v2, v3
	v_pk_mul_f32 v[2:3], v[96:97], v[44:45] op_sel_hi:[0,1]
	v_pk_mul_f32 v[6:7], v[96:97], v[54:55] op_sel_hi:[0,1]
	v_lshl_add_u64 v[4:5], v[62:63], 0, s[36:37]
	v_cvt_pk_bf16_f32 v2, v2, v3
	v_cvt_pk_bf16_f32 v3, v6, v7
	v_lshl_add_u32 v220, s36, 1, v176
	ds_write_b128 v220, v[0:3]
	v_pk_mul_f32 v[6:7], v[96:97], v[42:43] op_sel_hi:[0,1]
	s_xor_b64 s[6:7], s[4:5], -1
	v_pk_mul_f32 v[0:1], v[96:97], v[48:49] op_sel_hi:[0,1]
	v_pk_mul_f32 v[2:3], v[96:97], v[50:51] op_sel_hi:[0,1]
	v_cvt_pk_bf16_f32 v0, v0, v1
	v_cvt_pk_bf16_f32 v1, v2, v3
	v_pk_mul_f32 v[2:3], v[96:97], v[40:41] op_sel_hi:[0,1]
	v_cvt_pk_bf16_f32 v2, v2, v3
	v_cvt_pk_bf16_f32 v3, v6, v7
	ds_write_b128 v220, v[0:3] offset:16
	v_pk_mul_f32 v[6:7], v[96:97], v[46:47] op_sel_hi:[0,1]
	s_mov_b32 s8, 1
	v_pk_mul_f32 v[0:1], v[96:97], v[92:93] op_sel_hi:[0,1]
	v_pk_mul_f32 v[2:3], v[96:97], v[94:95] op_sel_hi:[0,1]
	v_cvt_pk_bf16_f32 v0, v0, v1
	v_cvt_pk_bf16_f32 v1, v2, v3
	v_pk_mul_f32 v[2:3], v[96:97], v[52:53] op_sel_hi:[0,1]
	v_cvt_pk_bf16_f32 v2, v2, v3
	v_cvt_pk_bf16_f32 v3, v6, v7
	ds_write_b128 v220, v[0:3] offset:32
	v_pk_mul_f32 v[6:7], v[96:97], v[34:35] op_sel_hi:[0,1]
	s_mov_b64 s[4:5], 0
	v_pk_mul_f32 v[0:1], v[96:97], v[36:37] op_sel_hi:[0,1]
	v_pk_mul_f32 v[2:3], v[96:97], v[38:39] op_sel_hi:[0,1]
	v_cvt_pk_bf16_f32 v0, v0, v1
	v_cvt_pk_bf16_f32 v1, v2, v3
	v_pk_mul_f32 v[2:3], v[96:97], v[32:33] op_sel_hi:[0,1]
	v_cvt_pk_bf16_f32 v2, v2, v3
	v_cvt_pk_bf16_f32 v3, v6, v7
	s_andn2_b64 vcc, exec, s[6:7]
	v_mov_b32_e32 v109, v244
	ds_write_b128 v220, v[0:3] offset:48
	v_mbcnt_lo_u32_b32 v204, -1, 0
	v_mbcnt_hi_u32_b32 v204, -1, v204
	v_lshrrev_b32_e32 v211, 2, v204
	v_and_b32_e32 v212, 3, v204
	v_sub_u32_e32 v216, v211, v204
	v_mul_i32_i24_e32 v224, 0x110, v216
	v_lshl_add_u32 v224, v212, 4, v224
	v_add_u32_e32 v224, v224, v220
	v_mul_i32_i24_e32 v234, 0x1600, v216
	v_lshl_add_u32 v234, v212, 4, v234
	s_waitcnt lgkmcnt(0)
	ds_read_b128 v[32:35], v224
	ds_read_b128 v[36:39], v224 offset:4352
	ds_read_b128 v[40:43], v224 offset:8704
	ds_read_b128 v[44:47], v224 offset:13056
	v_ashrrev_i32_e32 v235, 31, v234
	v_lshl_add_u64 v[250:251], v[4:5], 0, v[234:235]
	v_add_u32_e32 v234, 0x16000, v234
	s_waitcnt lgkmcnt(3)
	global_store_dwordx4 v[250:251], v[32:35], off
	v_ashrrev_i32_e32 v235, 31, v234
	v_lshl_add_u64 v[250:251], v[4:5], 0, v[234:235]
	v_add_u32_e32 v234, 0x16000, v234
	s_waitcnt lgkmcnt(2)
	global_store_dwordx4 v[250:251], v[36:39], off
	v_ashrrev_i32_e32 v235, 31, v234
	v_lshl_add_u64 v[250:251], v[4:5], 0, v[234:235]
	v_add_u32_e32 v234, 0x16000, v234
	s_waitcnt lgkmcnt(1)
	global_store_dwordx4 v[250:251], v[40:43], off
	v_ashrrev_i32_e32 v235, 31, v234
	v_lshl_add_u64 v[250:251], v[4:5], 0, v[234:235]
	s_waitcnt lgkmcnt(0)
	global_store_dwordx4 v[250:251], v[44:47], off
	s_cbranch_vccz .LBB0_290
